# gated-merge GEMM mid-K hook: gate addresses computed in a pre-pass, gate loads software-pipelined two steps ahead into spare registers with counted waits (was one load-wait round trip per step)
# speedup vs baseline: 1.0150x; 1.0113x over previous
.LBB0_263:
	v_mov_b32_e32 v130, v1
	v_mov_b32_e32 v131, v154
	s_and_b32 s22, s20, 0xc00
	v_add_u32_e32 v157, s64, v130
	v_lshl_add_u32 v166, v131, 3, s65
	v_add_u32_e32 v131, s93, v157
	v_mov_b64_e32 v[132:133], s[10:11]
	s_add_i32 s40, s22, 0xfffffc00
	v_add_u32_e32 v130, s92, v166
	v_mad_i64_i32 v[134:135], s[22:23], v131, s24, v[132:133]
	s_lshl_b64 s[22:23], s[40:41], 1
	v_ashrrev_i32_e32 v131, 31, v130
	v_lshl_add_u64 v[136:137], v[134:135], 0, s[22:23]
	v_lshlrev_b64 v[134:135], 1, v[130:131]
	v_lshl_add_u64 v[130:131], v[136:137], 0, v[134:135]
	v_mov_b32_e32 v206, v130
	v_mov_b32_e32 v207, v131
	v_add_u32_e32 v130, s94, v166
	v_ashrrev_i32_e32 v131, 31, v130
	v_lshlrev_b64 v[130:131], 1, v[130:131]
	v_lshl_add_u64 v[136:137], v[136:137], 0, v[130:131]
	v_mov_b32_e32 v208, v136
	v_mov_b32_e32 v209, v137
	v_add_u32_e32 v136, s95, v157
	v_mad_i64_i32 v[136:137], s[26:27], v136, s24, v[132:133]
	v_lshl_add_u64 v[136:137], v[136:137], 0, s[22:23]
	v_lshl_add_u64 v[162:163], v[136:137], 0, v[134:135]
	v_mov_b32_e32 v210, v162
	v_mov_b32_e32 v211, v163
	v_lshl_add_u64 v[136:137], v[136:137], 0, v[130:131]
	v_mov_b32_e32 v212, v136
	v_mov_b32_e32 v213, v137
	v_add_u32_e32 v136, s96, v157
	v_mad_i64_i32 v[136:137], s[26:27], v136, s24, v[132:133]
	v_lshl_add_u64 v[136:137], v[136:137], 0, s[22:23]
	v_lshl_add_u64 v[162:163], v[136:137], 0, v[134:135]
	v_mov_b32_e32 v214, v162
	v_mov_b32_e32 v215, v163
	v_lshl_add_u64 v[136:137], v[136:137], 0, v[130:131]
	v_mov_b32_e32 v216, v136
	v_mov_b32_e32 v217, v137
	v_add_u32_e32 v136, s97, v157
	v_mad_i64_i32 v[136:137], s[26:27], v136, s24, v[132:133]
	v_lshl_add_u64 v[136:137], v[136:137], 0, s[22:23]
	v_lshl_add_u64 v[162:163], v[136:137], 0, v[134:135]
	v_mov_b32_e32 v218, v162
	v_mov_b32_e32 v219, v163
	v_lshl_add_u64 v[136:137], v[136:137], 0, v[130:131]
	v_mov_b32_e32 v220, v136
	v_mov_b32_e32 v221, v137
	v_add_u32_e32 v136, s37, v157
	v_mad_i64_i32 v[136:137], s[26:27], v136, s24, v[132:133]
	v_lshl_add_u64 v[136:137], v[136:137], 0, s[22:23]
	v_lshl_add_u64 v[162:163], v[136:137], 0, v[134:135]
	v_mov_b32_e32 v222, v162
	v_mov_b32_e32 v223, v163
	v_lshl_add_u64 v[136:137], v[136:137], 0, v[130:131]
	v_mov_b32_e32 v226, v136
	v_mov_b32_e32 v227, v137
	v_add_u32_e32 v136, s89, v157
	v_mad_i64_i32 v[136:137], s[26:27], v136, s24, v[132:133]
	v_lshl_add_u64 v[136:137], v[136:137], 0, s[22:23]
	v_lshl_add_u64 v[162:163], v[136:137], 0, v[134:135]
	v_mov_b32_e32 v232, v162
	v_mov_b32_e32 v233, v163
	v_lshl_add_u64 v[136:137], v[136:137], 0, v[130:131]
	v_mov_b32_e32 v240, v136
	v_mov_b32_e32 v241, v137
	v_add_u32_e32 v136, s1, v157
	v_mad_i64_i32 v[136:137], s[26:27], v136, s24, v[132:133]
	v_lshl_add_u64 v[136:137], v[136:137], 0, s[22:23]
	v_lshl_add_u64 v[162:163], v[136:137], 0, v[134:135]
	v_mov_b32_e32 v242, v162
	v_mov_b32_e32 v243, v163
	v_lshl_add_u64 v[136:137], v[136:137], 0, v[130:131]
	v_mov_b32_e32 v244, v136
	v_mov_b32_e32 v245, v137
	v_add_u32_e32 v136, s0, v157
	v_mad_i64_i32 v[132:133], s[26:27], v136, s24, v[132:133]
	v_lshl_add_u64 v[132:133], v[132:133], 0, s[22:23]
	v_lshl_add_u64 v[158:159], v[132:133], 0, v[134:135]
	v_mov_b32_e32 v246, v158
	v_mov_b32_e32 v247, v159
	v_lshl_add_u64 v[134:135], v[132:133], 0, v[130:131]
	v_mov_b32_e32 v248, v134
	v_mov_b32_e32 v249, v135
	global_load_dwordx4 v[174:177], v[206:207], off
	global_load_dwordx4 v[178:181], v[206:207], off offset:2048
	global_load_dwordx4 v[182:185], v[208:209], off
	global_load_dwordx4 v[186:189], v[208:209], off offset:2048
	global_load_dwordx4 v[190:193], v[210:211], off
	global_load_dwordx4 v[194:197], v[210:211], off offset:2048
	s_waitcnt vmcnt(4)
	v_lshlrev_b32_e32 v130, 16, v178
	v_and_b32_e32 v131, 0xffff0000, v178
	v_rcp_f32_e32 v130, v130
	v_rcp_f32_e32 v131, v131
	v_lshlrev_b32_e32 v167, 16, v179
	v_and_b32_e32 v168, 0xffff0000, v179
	v_lshlrev_b32_e32 v162, 16, v180
	v_and_b32_e32 v163, 0xffff0000, v180
	v_rcp_f32_e32 v162, v162
	v_rcp_f32_e32 v163, v163
	v_lshlrev_b32_e32 v169, 16, v181
	v_and_b32_e32 v170, 0xffff0000, v181
	v_lshlrev_b32_e32 v164, 16, v174
	v_and_b32_e32 v165, 0xffff0000, v174
	v_pk_mul_f32 v[130:131], v[130:131], v[164:165]
	v_rcp_f32_e32 v158, v169
	v_pk_mul_f32 v[126:127], v[126:127], v[130:131]
	v_lshlrev_b32_e32 v130, 16, v176
	v_and_b32_e32 v131, 0xffff0000, v176
	v_pk_mul_f32 v[130:131], v[162:163], v[130:131]
	v_lshlrev_b32_e32 v162, 16, v175
	v_pk_mul_f32 v[122:123], v[122:123], v[130:131]
	v_rcp_f32_e32 v130, v167
	v_rcp_f32_e32 v131, v168
	v_and_b32_e32 v163, 0xffff0000, v175
	v_rcp_f32_e32 v159, v170
	v_pk_mul_f32 v[130:131], v[130:131], v[162:163]
	s_nop 0
	v_pk_mul_f32 v[128:129], v[128:129], v[130:131]
	v_lshlrev_b32_e32 v130, 16, v177
	v_and_b32_e32 v131, 0xffff0000, v177
	v_pk_mul_f32 v[130:131], v[158:159], v[130:131]
	s_nop 0
	v_pk_mul_f32 v[124:125], v[124:125], v[130:131]
	global_load_dwordx4 v[198:201], v[212:213], off
	global_load_dwordx4 v[202:205], v[212:213], off offset:2048
	s_waitcnt vmcnt(4)
	v_lshlrev_b32_e32 v136, 16, v186
	v_and_b32_e32 v137, 0xffff0000, v186
	v_rcp_f32_e32 v136, v136
	v_rcp_f32_e32 v137, v137
	v_lshlrev_b32_e32 v166, 16, v187
	v_and_b32_e32 v167, 0xffff0000, v187
	v_lshlrev_b32_e32 v162, 16, v188
	v_and_b32_e32 v163, 0xffff0000, v188
	v_rcp_f32_e32 v162, v162
	v_rcp_f32_e32 v163, v163
	v_lshlrev_b32_e32 v168, 16, v189
	v_and_b32_e32 v169, 0xffff0000, v189
	v_lshlrev_b32_e32 v164, 16, v182
	v_and_b32_e32 v165, 0xffff0000, v182
	v_pk_mul_f32 v[136:137], v[136:137], v[164:165]
	v_rcp_f32_e32 v158, v168
	v_pk_mul_f32 v[118:119], v[118:119], v[136:137]
	v_lshlrev_b32_e32 v136, 16, v184
	v_and_b32_e32 v137, 0xffff0000, v184
	v_pk_mul_f32 v[136:137], v[162:163], v[136:137]
	v_lshlrev_b32_e32 v162, 16, v183
	v_pk_mul_f32 v[114:115], v[114:115], v[136:137]
	v_rcp_f32_e32 v136, v166
	v_rcp_f32_e32 v137, v167
	v_and_b32_e32 v163, 0xffff0000, v183
	v_rcp_f32_e32 v159, v169
	v_pk_mul_f32 v[136:137], v[136:137], v[162:163]
	s_nop 0
	v_pk_mul_f32 v[120:121], v[120:121], v[136:137]
	v_lshlrev_b32_e32 v136, 16, v185
	v_and_b32_e32 v137, 0xffff0000, v185
	v_pk_mul_f32 v[136:137], v[158:159], v[136:137]
	s_nop 0
	v_pk_mul_f32 v[116:117], v[116:117], v[136:137]
	global_load_dwordx4 v[174:177], v[214:215], off
	global_load_dwordx4 v[178:181], v[214:215], off offset:2048
	s_waitcnt vmcnt(4)
	s_nop 0
	v_lshlrev_b32_e32 v166, 16, v194
	v_and_b32_e32 v167, 0xffff0000, v194
	v_lshlrev_b32_e32 v168, 16, v195
	v_and_b32_e32 v169, 0xffff0000, v195
	v_lshlrev_b32_e32 v163, 16, v196
	v_and_b32_e32 v170, 0xffff0000, v196
	v_rcp_f32_e32 v162, v166
	v_rcp_f32_e32 v164, v163
	v_rcp_f32_e32 v163, v167
	v_lshlrev_b32_e32 v171, 16, v197
	v_and_b32_e32 v172, 0xffff0000, v197
	v_rcp_f32_e32 v165, v170
	v_lshlrev_b32_e32 v166, 16, v190
	v_and_b32_e32 v167, 0xffff0000, v190
	v_pk_mul_f32 v[162:163], v[162:163], v[166:167]
	v_rcp_f32_e32 v158, v171
	v_pk_mul_f32 v[110:111], v[110:111], v[162:163]
	v_lshlrev_b32_e32 v162, 16, v192
	v_and_b32_e32 v163, 0xffff0000, v192
	v_pk_mul_f32 v[162:163], v[164:165], v[162:163]
	v_lshlrev_b32_e32 v164, 16, v191
	v_pk_mul_f32 v[106:107], v[106:107], v[162:163]
	v_rcp_f32_e32 v162, v168
	v_rcp_f32_e32 v163, v169
	v_and_b32_e32 v165, 0xffff0000, v191
	v_rcp_f32_e32 v159, v172
	v_lshlrev_b32_e32 v160, 16, v193
	v_and_b32_e32 v161, 0xffff0000, v193
	v_pk_mul_f32 v[162:163], v[162:163], v[164:165]
	v_pk_mul_f32 v[158:159], v[158:159], v[160:161]
	v_pk_mul_f32 v[112:113], v[112:113], v[162:163]
	v_pk_mul_f32 v[108:109], v[108:109], v[158:159]
	global_load_dwordx4 v[182:185], v[216:217], off
	global_load_dwordx4 v[186:189], v[216:217], off offset:2048
	s_waitcnt vmcnt(4)
	v_lshlrev_b32_e32 v136, 16, v202
	v_and_b32_e32 v137, 0xffff0000, v202
	v_rcp_f32_e32 v136, v136
	v_rcp_f32_e32 v137, v137
	v_lshlrev_b32_e32 v166, 16, v203
	v_and_b32_e32 v167, 0xffff0000, v203
	v_lshlrev_b32_e32 v162, 16, v204
	v_and_b32_e32 v163, 0xffff0000, v204
	v_rcp_f32_e32 v162, v162
	v_rcp_f32_e32 v163, v163
	v_lshlrev_b32_e32 v168, 16, v205
	v_and_b32_e32 v169, 0xffff0000, v205
	v_lshlrev_b32_e32 v164, 16, v198
	v_and_b32_e32 v165, 0xffff0000, v198
	v_pk_mul_f32 v[136:137], v[136:137], v[164:165]
	v_rcp_f32_e32 v158, v168
	v_pk_mul_f32 v[102:103], v[102:103], v[136:137]
	v_lshlrev_b32_e32 v136, 16, v200
	v_and_b32_e32 v137, 0xffff0000, v200
	v_pk_mul_f32 v[136:137], v[162:163], v[136:137]
	v_lshlrev_b32_e32 v162, 16, v199
	v_pk_mul_f32 v[98:99], v[98:99], v[136:137]
	v_rcp_f32_e32 v136, v166
	v_rcp_f32_e32 v137, v167
	v_and_b32_e32 v163, 0xffff0000, v199
	v_rcp_f32_e32 v159, v169
	v_pk_mul_f32 v[136:137], v[136:137], v[162:163]
	s_nop 0
	v_pk_mul_f32 v[104:105], v[104:105], v[136:137]
	v_lshlrev_b32_e32 v136, 16, v201
	v_and_b32_e32 v137, 0xffff0000, v201
	v_pk_mul_f32 v[136:137], v[158:159], v[136:137]
	s_nop 0
	v_pk_mul_f32 v[100:101], v[100:101], v[136:137]
	global_load_dwordx4 v[190:193], v[218:219], off
	global_load_dwordx4 v[194:197], v[218:219], off offset:2048
	s_waitcnt vmcnt(4)
	s_nop 0
	v_lshlrev_b32_e32 v166, 16, v178
	v_and_b32_e32 v167, 0xffff0000, v178
	v_lshlrev_b32_e32 v168, 16, v179
	v_and_b32_e32 v169, 0xffff0000, v179
	v_lshlrev_b32_e32 v163, 16, v180
	v_and_b32_e32 v170, 0xffff0000, v180
	v_rcp_f32_e32 v162, v166
	v_rcp_f32_e32 v164, v163
	v_rcp_f32_e32 v163, v167
	v_lshlrev_b32_e32 v171, 16, v181
	v_and_b32_e32 v172, 0xffff0000, v181
	v_rcp_f32_e32 v165, v170
	v_lshlrev_b32_e32 v166, 16, v174
	v_and_b32_e32 v167, 0xffff0000, v174
	v_pk_mul_f32 v[162:163], v[162:163], v[166:167]
	v_rcp_f32_e32 v158, v171
	v_pk_mul_f32 v[94:95], v[94:95], v[162:163]
	v_lshlrev_b32_e32 v162, 16, v176
	v_and_b32_e32 v163, 0xffff0000, v176
	v_pk_mul_f32 v[162:163], v[164:165], v[162:163]
	v_lshlrev_b32_e32 v164, 16, v175
	v_pk_mul_f32 v[90:91], v[90:91], v[162:163]
	v_rcp_f32_e32 v162, v168
	v_rcp_f32_e32 v163, v169
	v_and_b32_e32 v165, 0xffff0000, v175
	v_rcp_f32_e32 v159, v172
	v_lshlrev_b32_e32 v160, 16, v177
	v_and_b32_e32 v161, 0xffff0000, v177
	v_pk_mul_f32 v[162:163], v[162:163], v[164:165]
	v_pk_mul_f32 v[158:159], v[158:159], v[160:161]
	v_pk_mul_f32 v[96:97], v[96:97], v[162:163]
	v_pk_mul_f32 v[92:93], v[92:93], v[158:159]
	global_load_dwordx4 v[198:201], v[220:221], off
	global_load_dwordx4 v[202:205], v[220:221], off offset:2048
	s_waitcnt vmcnt(4)
	v_lshlrev_b32_e32 v136, 16, v186
	v_and_b32_e32 v137, 0xffff0000, v186
	v_rcp_f32_e32 v136, v136
	v_rcp_f32_e32 v137, v137
	v_lshlrev_b32_e32 v166, 16, v187
	v_and_b32_e32 v167, 0xffff0000, v187
	v_lshlrev_b32_e32 v162, 16, v188
	v_and_b32_e32 v163, 0xffff0000, v188
	v_rcp_f32_e32 v162, v162
	v_rcp_f32_e32 v163, v163
	v_lshlrev_b32_e32 v168, 16, v189
	v_and_b32_e32 v169, 0xffff0000, v189
	v_lshlrev_b32_e32 v164, 16, v182
	v_and_b32_e32 v165, 0xffff0000, v182
	v_pk_mul_f32 v[136:137], v[136:137], v[164:165]
	v_rcp_f32_e32 v158, v168
	v_pk_mul_f32 v[86:87], v[86:87], v[136:137]
	v_lshlrev_b32_e32 v136, 16, v184
	v_and_b32_e32 v137, 0xffff0000, v184
	v_pk_mul_f32 v[136:137], v[162:163], v[136:137]
	v_lshlrev_b32_e32 v162, 16, v183
	v_pk_mul_f32 v[82:83], v[82:83], v[136:137]
	v_rcp_f32_e32 v136, v166
	v_rcp_f32_e32 v137, v167
	v_and_b32_e32 v163, 0xffff0000, v183
	v_rcp_f32_e32 v159, v169
	v_pk_mul_f32 v[136:137], v[136:137], v[162:163]
	s_nop 0
	v_pk_mul_f32 v[88:89], v[88:89], v[136:137]
	v_lshlrev_b32_e32 v136, 16, v185
	v_and_b32_e32 v137, 0xffff0000, v185
	v_pk_mul_f32 v[136:137], v[158:159], v[136:137]
	s_nop 0
	v_pk_mul_f32 v[84:85], v[84:85], v[136:137]
	global_load_dwordx4 v[174:177], v[222:223], off
	global_load_dwordx4 v[178:181], v[222:223], off offset:2048
	s_waitcnt vmcnt(4)
	s_nop 0
	v_lshlrev_b32_e32 v166, 16, v194
	v_and_b32_e32 v167, 0xffff0000, v194
	v_lshlrev_b32_e32 v168, 16, v195
	v_and_b32_e32 v169, 0xffff0000, v195
	v_lshlrev_b32_e32 v163, 16, v196
	v_and_b32_e32 v170, 0xffff0000, v196
	v_rcp_f32_e32 v162, v166
	v_rcp_f32_e32 v164, v163
	v_rcp_f32_e32 v163, v167
	v_lshlrev_b32_e32 v171, 16, v197
	v_and_b32_e32 v172, 0xffff0000, v197
	v_rcp_f32_e32 v165, v170
	v_lshlrev_b32_e32 v166, 16, v190
	v_and_b32_e32 v167, 0xffff0000, v190
	v_pk_mul_f32 v[162:163], v[162:163], v[166:167]
	v_rcp_f32_e32 v158, v171
	v_pk_mul_f32 v[78:79], v[78:79], v[162:163]
	v_lshlrev_b32_e32 v162, 16, v192
	v_and_b32_e32 v163, 0xffff0000, v192
	v_pk_mul_f32 v[162:163], v[164:165], v[162:163]
	v_lshlrev_b32_e32 v164, 16, v191
	v_pk_mul_f32 v[74:75], v[74:75], v[162:163]
	v_rcp_f32_e32 v162, v168
	v_rcp_f32_e32 v163, v169
	v_and_b32_e32 v165, 0xffff0000, v191
	v_rcp_f32_e32 v159, v172
	v_lshlrev_b32_e32 v160, 16, v193
	v_and_b32_e32 v161, 0xffff0000, v193
	v_pk_mul_f32 v[162:163], v[162:163], v[164:165]
	v_pk_mul_f32 v[158:159], v[158:159], v[160:161]
	v_pk_mul_f32 v[80:81], v[80:81], v[162:163]
	v_pk_mul_f32 v[76:77], v[76:77], v[158:159]
	global_load_dwordx4 v[182:185], v[226:227], off
	global_load_dwordx4 v[186:189], v[226:227], off offset:2048
	s_waitcnt vmcnt(4)
	v_lshlrev_b32_e32 v136, 16, v202
	v_and_b32_e32 v137, 0xffff0000, v202
	v_rcp_f32_e32 v136, v136
	v_rcp_f32_e32 v137, v137
	v_lshlrev_b32_e32 v166, 16, v203
	v_and_b32_e32 v167, 0xffff0000, v203
	v_lshlrev_b32_e32 v162, 16, v204
	v_and_b32_e32 v163, 0xffff0000, v204
	v_rcp_f32_e32 v162, v162
	v_rcp_f32_e32 v163, v163
	v_lshlrev_b32_e32 v168, 16, v205
	v_and_b32_e32 v169, 0xffff0000, v205
	v_lshlrev_b32_e32 v164, 16, v198
	v_and_b32_e32 v165, 0xffff0000, v198
	v_pk_mul_f32 v[136:137], v[136:137], v[164:165]
	v_rcp_f32_e32 v158, v168
	v_pk_mul_f32 v[70:71], v[70:71], v[136:137]
	v_lshlrev_b32_e32 v136, 16, v200
	v_and_b32_e32 v137, 0xffff0000, v200
	v_pk_mul_f32 v[136:137], v[162:163], v[136:137]
	v_lshlrev_b32_e32 v162, 16, v199
	v_pk_mul_f32 v[66:67], v[66:67], v[136:137]
	v_rcp_f32_e32 v136, v166
	v_rcp_f32_e32 v137, v167
	v_and_b32_e32 v163, 0xffff0000, v199
	v_rcp_f32_e32 v159, v169
	v_pk_mul_f32 v[136:137], v[136:137], v[162:163]
	s_nop 0
	v_pk_mul_f32 v[72:73], v[72:73], v[136:137]
	v_lshlrev_b32_e32 v136, 16, v201
	v_and_b32_e32 v137, 0xffff0000, v201
	v_pk_mul_f32 v[136:137], v[158:159], v[136:137]
	s_nop 0
	v_pk_mul_f32 v[68:69], v[68:69], v[136:137]
	global_load_dwordx4 v[190:193], v[232:233], off
	global_load_dwordx4 v[194:197], v[232:233], off offset:2048
	s_waitcnt vmcnt(4)
	s_nop 0
	v_lshlrev_b32_e32 v166, 16, v178
	v_and_b32_e32 v167, 0xffff0000, v178
	v_lshlrev_b32_e32 v168, 16, v179
	v_and_b32_e32 v169, 0xffff0000, v179
	v_lshlrev_b32_e32 v163, 16, v180
	v_and_b32_e32 v170, 0xffff0000, v180
	v_rcp_f32_e32 v162, v166
	v_rcp_f32_e32 v164, v163
	v_rcp_f32_e32 v163, v167
	v_lshlrev_b32_e32 v171, 16, v181
	v_and_b32_e32 v172, 0xffff0000, v181
	v_rcp_f32_e32 v165, v170
	v_lshlrev_b32_e32 v166, 16, v174
	v_and_b32_e32 v167, 0xffff0000, v174
	v_pk_mul_f32 v[162:163], v[162:163], v[166:167]
	v_rcp_f32_e32 v158, v171
	v_pk_mul_f32 v[62:63], v[62:63], v[162:163]
	v_lshlrev_b32_e32 v162, 16, v176
	v_and_b32_e32 v163, 0xffff0000, v176
	v_pk_mul_f32 v[162:163], v[164:165], v[162:163]
	v_lshlrev_b32_e32 v164, 16, v175
	v_pk_mul_f32 v[58:59], v[58:59], v[162:163]
	v_rcp_f32_e32 v162, v168
	v_rcp_f32_e32 v163, v169
	v_and_b32_e32 v165, 0xffff0000, v175
	v_rcp_f32_e32 v159, v172
	v_lshlrev_b32_e32 v160, 16, v177
	v_and_b32_e32 v161, 0xffff0000, v177
	v_pk_mul_f32 v[162:163], v[162:163], v[164:165]
	v_pk_mul_f32 v[158:159], v[158:159], v[160:161]
	v_pk_mul_f32 v[64:65], v[64:65], v[162:163]
	v_pk_mul_f32 v[60:61], v[60:61], v[158:159]
	global_load_dwordx4 v[198:201], v[240:241], off
	global_load_dwordx4 v[202:205], v[240:241], off offset:2048
	s_waitcnt vmcnt(4)
	v_lshlrev_b32_e32 v136, 16, v186
	v_and_b32_e32 v137, 0xffff0000, v186
	v_rcp_f32_e32 v136, v136
	v_rcp_f32_e32 v137, v137
	v_lshlrev_b32_e32 v166, 16, v187
	v_and_b32_e32 v167, 0xffff0000, v187
	v_lshlrev_b32_e32 v162, 16, v188
	v_and_b32_e32 v163, 0xffff0000, v188
	v_rcp_f32_e32 v162, v162
	v_rcp_f32_e32 v163, v163
	v_lshlrev_b32_e32 v168, 16, v189
	v_and_b32_e32 v169, 0xffff0000, v189
	v_lshlrev_b32_e32 v164, 16, v182
	v_and_b32_e32 v165, 0xffff0000, v182
	v_pk_mul_f32 v[136:137], v[136:137], v[164:165]
	v_rcp_f32_e32 v158, v168
	v_pk_mul_f32 v[54:55], v[54:55], v[136:137]
	v_lshlrev_b32_e32 v136, 16, v184
	v_and_b32_e32 v137, 0xffff0000, v184
	v_pk_mul_f32 v[136:137], v[162:163], v[136:137]
	v_lshlrev_b32_e32 v162, 16, v183
	v_pk_mul_f32 v[50:51], v[50:51], v[136:137]
	v_rcp_f32_e32 v136, v166
	v_rcp_f32_e32 v137, v167
	v_and_b32_e32 v163, 0xffff0000, v183
	v_rcp_f32_e32 v159, v169
	v_pk_mul_f32 v[136:137], v[136:137], v[162:163]
	s_nop 0
	v_pk_mul_f32 v[56:57], v[56:57], v[136:137]
	v_lshlrev_b32_e32 v136, 16, v185
	v_and_b32_e32 v137, 0xffff0000, v185
	v_pk_mul_f32 v[136:137], v[158:159], v[136:137]
	s_nop 0
	v_pk_mul_f32 v[52:53], v[52:53], v[136:137]
	global_load_dwordx4 v[174:177], v[242:243], off
	global_load_dwordx4 v[178:181], v[242:243], off offset:2048
	s_waitcnt vmcnt(4)
	s_nop 0
	v_lshlrev_b32_e32 v166, 16, v194
	v_and_b32_e32 v167, 0xffff0000, v194
	v_lshlrev_b32_e32 v168, 16, v195
	v_and_b32_e32 v169, 0xffff0000, v195
	v_lshlrev_b32_e32 v163, 16, v196
	v_and_b32_e32 v170, 0xffff0000, v196
	v_rcp_f32_e32 v162, v166
	v_rcp_f32_e32 v164, v163
	v_rcp_f32_e32 v163, v167
	v_lshlrev_b32_e32 v171, 16, v197
	v_and_b32_e32 v172, 0xffff0000, v197
	v_rcp_f32_e32 v165, v170
	v_lshlrev_b32_e32 v166, 16, v190
	v_and_b32_e32 v167, 0xffff0000, v190
	v_pk_mul_f32 v[162:163], v[162:163], v[166:167]
	v_rcp_f32_e32 v158, v171
	v_pk_mul_f32 v[46:47], v[46:47], v[162:163]
	v_lshlrev_b32_e32 v162, 16, v192
	v_and_b32_e32 v163, 0xffff0000, v192
	v_pk_mul_f32 v[162:163], v[164:165], v[162:163]
	v_lshlrev_b32_e32 v164, 16, v191
	v_pk_mul_f32 v[42:43], v[42:43], v[162:163]
	v_rcp_f32_e32 v162, v168
	v_rcp_f32_e32 v163, v169
	v_and_b32_e32 v165, 0xffff0000, v191
	v_rcp_f32_e32 v159, v172
	v_lshlrev_b32_e32 v160, 16, v193
	v_and_b32_e32 v161, 0xffff0000, v193
	v_pk_mul_f32 v[162:163], v[162:163], v[164:165]
	v_pk_mul_f32 v[158:159], v[158:159], v[160:161]
	v_pk_mul_f32 v[48:49], v[48:49], v[162:163]
	v_pk_mul_f32 v[44:45], v[44:45], v[158:159]
	global_load_dwordx4 v[182:185], v[244:245], off
	global_load_dwordx4 v[186:189], v[244:245], off offset:2048
	s_waitcnt vmcnt(4)
	v_lshlrev_b32_e32 v136, 16, v202
	v_and_b32_e32 v137, 0xffff0000, v202
	v_rcp_f32_e32 v136, v136
	v_rcp_f32_e32 v137, v137
	v_lshlrev_b32_e32 v166, 16, v203
	v_and_b32_e32 v167, 0xffff0000, v203
	v_lshlrev_b32_e32 v162, 16, v204
	v_and_b32_e32 v163, 0xffff0000, v204
	v_rcp_f32_e32 v162, v162
	v_rcp_f32_e32 v163, v163
	v_lshlrev_b32_e32 v168, 16, v205
	v_and_b32_e32 v169, 0xffff0000, v205
	v_lshlrev_b32_e32 v164, 16, v198
	v_and_b32_e32 v165, 0xffff0000, v198
	v_pk_mul_f32 v[136:137], v[136:137], v[164:165]
	v_rcp_f32_e32 v158, v168
	v_pk_mul_f32 v[38:39], v[38:39], v[136:137]
	v_lshlrev_b32_e32 v136, 16, v200
	v_and_b32_e32 v137, 0xffff0000, v200
	v_pk_mul_f32 v[136:137], v[162:163], v[136:137]
	v_lshlrev_b32_e32 v162, 16, v199
	v_pk_mul_f32 v[34:35], v[34:35], v[136:137]
	v_rcp_f32_e32 v136, v166
	v_rcp_f32_e32 v137, v167
	v_and_b32_e32 v163, 0xffff0000, v199
	v_rcp_f32_e32 v159, v169
	v_pk_mul_f32 v[136:137], v[136:137], v[162:163]
	s_nop 0
	v_pk_mul_f32 v[40:41], v[40:41], v[136:137]
	v_lshlrev_b32_e32 v136, 16, v201
	v_and_b32_e32 v137, 0xffff0000, v201
	v_pk_mul_f32 v[136:137], v[158:159], v[136:137]
	s_nop 0
	v_pk_mul_f32 v[36:37], v[36:37], v[136:137]
	global_load_dwordx4 v[190:193], v[246:247], off
	global_load_dwordx4 v[194:197], v[246:247], off offset:2048
	s_waitcnt vmcnt(4)
	s_nop 0
	v_lshlrev_b32_e32 v166, 16, v178
	v_and_b32_e32 v167, 0xffff0000, v178
	v_lshlrev_b32_e32 v168, 16, v179
	v_and_b32_e32 v169, 0xffff0000, v179
	v_lshlrev_b32_e32 v163, 16, v180
	v_and_b32_e32 v170, 0xffff0000, v180
	v_rcp_f32_e32 v162, v166
	v_rcp_f32_e32 v164, v163
	v_rcp_f32_e32 v163, v167
	v_lshlrev_b32_e32 v171, 16, v181
	v_and_b32_e32 v172, 0xffff0000, v181
	v_rcp_f32_e32 v165, v170
	v_lshlrev_b32_e32 v166, 16, v174
	v_and_b32_e32 v167, 0xffff0000, v174
	v_pk_mul_f32 v[162:163], v[162:163], v[166:167]
	v_rcp_f32_e32 v158, v171
	v_pk_mul_f32 v[30:31], v[30:31], v[162:163]
	v_lshlrev_b32_e32 v162, 16, v176
	v_and_b32_e32 v163, 0xffff0000, v176
	v_pk_mul_f32 v[162:163], v[164:165], v[162:163]
	v_lshlrev_b32_e32 v164, 16, v175
	v_pk_mul_f32 v[26:27], v[26:27], v[162:163]
	v_rcp_f32_e32 v162, v168
	v_rcp_f32_e32 v163, v169
	v_and_b32_e32 v165, 0xffff0000, v175
	v_rcp_f32_e32 v159, v172
	v_lshlrev_b32_e32 v160, 16, v177
	v_and_b32_e32 v161, 0xffff0000, v177
	v_pk_mul_f32 v[162:163], v[162:163], v[164:165]
	v_pk_mul_f32 v[158:159], v[158:159], v[160:161]
	v_pk_mul_f32 v[32:33], v[32:33], v[162:163]
	v_pk_mul_f32 v[28:29], v[28:29], v[158:159]
	global_load_dwordx4 v[198:201], v[248:249], off
	global_load_dwordx4 v[202:205], v[248:249], off offset:2048
	s_waitcnt vmcnt(4)
	v_lshlrev_b32_e32 v136, 16, v186
	v_and_b32_e32 v137, 0xffff0000, v186
	v_rcp_f32_e32 v136, v136
	v_rcp_f32_e32 v137, v137
	v_lshlrev_b32_e32 v166, 16, v187
	v_and_b32_e32 v167, 0xffff0000, v187
	v_lshlrev_b32_e32 v162, 16, v188
	v_and_b32_e32 v163, 0xffff0000, v188
	v_rcp_f32_e32 v162, v162
	v_rcp_f32_e32 v163, v163
	v_lshlrev_b32_e32 v168, 16, v189
	v_and_b32_e32 v169, 0xffff0000, v189
	v_lshlrev_b32_e32 v164, 16, v182
	v_and_b32_e32 v165, 0xffff0000, v182
	v_pk_mul_f32 v[136:137], v[136:137], v[164:165]
	v_rcp_f32_e32 v158, v168
	v_pk_mul_f32 v[22:23], v[22:23], v[136:137]
	v_lshlrev_b32_e32 v136, 16, v184
	v_and_b32_e32 v137, 0xffff0000, v184
	v_pk_mul_f32 v[136:137], v[162:163], v[136:137]
	v_lshlrev_b32_e32 v162, 16, v183
	v_pk_mul_f32 v[18:19], v[18:19], v[136:137]
	v_rcp_f32_e32 v136, v166
	v_rcp_f32_e32 v137, v167
	v_and_b32_e32 v163, 0xffff0000, v183
	v_rcp_f32_e32 v159, v169
	v_pk_mul_f32 v[136:137], v[136:137], v[162:163]
	s_nop 0
	v_pk_mul_f32 v[24:25], v[24:25], v[136:137]
	v_lshlrev_b32_e32 v136, 16, v185
	v_and_b32_e32 v137, 0xffff0000, v185
	v_pk_mul_f32 v[136:137], v[158:159], v[136:137]
	s_nop 0
	v_pk_mul_f32 v[20:21], v[20:21], v[136:137]
	s_waitcnt vmcnt(2)
	s_nop 0
	v_and_b32_e32 v163, 0xffff0000, v190
	v_lshlrev_b32_e32 v157, 16, v194
	v_and_b32_e32 v162, 0xffff0000, v194
	v_lshlrev_b32_e32 v164, 16, v195
	v_and_b32_e32 v165, 0xffff0000, v195
	v_lshlrev_b32_e32 v159, 16, v196
	v_and_b32_e32 v166, 0xffff0000, v196
	v_rcp_f32_e32 v158, v157
	v_rcp_f32_e32 v160, v159
	v_rcp_f32_e32 v159, v162
	v_lshlrev_b32_e32 v167, 16, v197
	v_and_b32_e32 v168, 0xffff0000, v197
	v_rcp_f32_e32 v161, v166
	v_lshlrev_b32_e32 v162, 16, v190
	v_pk_mul_f32 v[158:159], v[158:159], v[162:163]
	v_rcp_f32_e32 v134, v167
	v_pk_mul_f32 v[14:15], v[14:15], v[158:159]
	v_lshlrev_b32_e32 v158, 16, v192
	v_and_b32_e32 v159, 0xffff0000, v192
	v_pk_mul_f32 v[158:159], v[160:161], v[158:159]
	v_lshlrev_b32_e32 v160, 16, v191
	v_and_b32_e32 v161, 0xffff0000, v191
	v_rcp_f32_e32 v135, v168
	v_lshlrev_b32_e32 v136, 16, v193
	v_and_b32_e32 v137, 0xffff0000, v193
	v_pk_mul_f32 v[10:11], v[10:11], v[158:159]
	v_pk_mul_f32 v[134:135], v[134:135], v[136:137]
	v_rcp_f32_e32 v158, v164
	v_pk_mul_f32 v[12:13], v[12:13], v[134:135]
	s_waitcnt vmcnt(0)
	s_nop 0
	v_rcp_f32_e32 v159, v165
	v_lshlrev_b32_e32 v157, 16, v202
	v_pk_mul_f32 v[158:159], v[158:159], v[160:161]
	v_lshlrev_b32_e32 v160, 16, v203
	v_pk_mul_f32 v[16:17], v[16:17], v[158:159]
	v_and_b32_e32 v158, 0xffff0000, v202
	v_and_b32_e32 v161, 0xffff0000, v203
	v_lshlrev_b32_e32 v135, 16, v204
	v_and_b32_e32 v162, 0xffff0000, v204
	v_rcp_f32_e32 v134, v157
	v_rcp_f32_e32 v136, v135
	v_rcp_f32_e32 v135, v158
	v_lshlrev_b32_e32 v163, 16, v205
	v_and_b32_e32 v164, 0xffff0000, v205
	v_rcp_f32_e32 v137, v162
	v_lshlrev_b32_e32 v158, 16, v198
	v_and_b32_e32 v159, 0xffff0000, v198
	v_pk_mul_f32 v[134:135], v[134:135], v[158:159]
	v_rcp_f32_e32 v130, v163
	v_pk_mul_f32 v[6:7], v[6:7], v[134:135]
	v_lshlrev_b32_e32 v134, 16, v200
	v_and_b32_e32 v135, 0xffff0000, v200
	v_pk_mul_f32 v[134:135], v[136:137], v[134:135]
	v_lshlrev_b32_e32 v136, 16, v199
	v_pk_mul_f32 v[2:3], v[2:3], v[134:135]
	v_rcp_f32_e32 v134, v160
	v_rcp_f32_e32 v135, v161
	v_and_b32_e32 v137, 0xffff0000, v199
	v_rcp_f32_e32 v131, v164
	v_lshlrev_b32_e32 v132, 16, v201
	v_and_b32_e32 v133, 0xffff0000, v201
	v_pk_mul_f32 v[134:135], v[134:135], v[136:137]
	v_pk_mul_f32 v[130:131], v[130:131], v[132:133]
	v_pk_mul_f32 v[8:9], v[8:9], v[134:135]
	v_pk_mul_f32 v[4:5], v[4:5], v[130:131]
	s_branch .LBB0_255
